# GEMM unit seams (all 5 phases): trailing wave half runs next-unit scheduling + accumulator zeroing before its re-offset barrier instead of after it
# baseline (speedup 1.0000x reference)
.LBB0_140:
	s_andn2_b64 vcc, exec, s[4:5]
	s_cbranch_vccnz .LBB0_123
	s_branch .Lthp1_123

.Lthp1_131:
	s_ashr_i32 s57, s56, 31
	s_lshl_b64 s[58:59], s[56:57], 21
	s_add_u32 s58, s8, s58
	s_addc_u32 s59, s9, s59
	s_and_b64 s[70:71], s[0:1], exec
	s_cselect_b32 s57, s59, s77
	s_cselect_b32 s95, s58, s76
	s_ashr_i32 s55, s54, 31
	s_lshl_b64 s[70:71], s[54:55], 21
	s_add_u32 s70, s14, s70
	s_addc_u32 s71, s15, s71
	s_and_b64 s[78:79], s[0:1], exec
	s_cselect_b32 s55, s71, s75
	s_cselect_b32 s96, s70, s74
	s_add_u32 s97, s74, 0x1000
	s_addc_u32 vcc_lo, s75, 0
	s_add_u32 s74, s76, 0x100080
	v_mov_b64_e32 v[0:1], 0
	v_mov_b64_e32 v[2:3], 0
	v_mov_b64_e32 v[4:5], 0
	v_mov_b64_e32 v[6:7], 0
	v_mov_b64_e32 v[8:9], 0
	v_mov_b64_e32 v[10:11], 0
	v_mov_b64_e32 v[12:13], 0
	v_mov_b64_e32 v[14:15], 0
	v_mov_b64_e32 v[16:17], 0
	v_mov_b64_e32 v[18:19], 0
	v_mov_b64_e32 v[20:21], 0
	v_mov_b64_e32 v[22:23], 0
	v_mov_b64_e32 v[24:25], 0
	v_mov_b64_e32 v[26:27], 0
	v_mov_b64_e32 v[28:29], 0
	v_mov_b64_e32 v[30:31], 0
	v_mov_b64_e32 v[32:33], 0
	v_mov_b64_e32 v[34:35], 0
	v_mov_b64_e32 v[36:37], 0
	v_mov_b64_e32 v[38:39], 0
	v_mov_b64_e32 v[40:41], 0
	v_mov_b64_e32 v[42:43], 0
	v_mov_b64_e32 v[44:45], 0
	v_mov_b64_e32 v[46:47], 0
	v_mov_b64_e32 v[48:49], 0
	v_mov_b64_e32 v[50:51], 0
	v_mov_b64_e32 v[52:53], 0
	v_mov_b64_e32 v[54:55], 0
	v_mov_b64_e32 v[56:57], 0
	v_mov_b64_e32 v[58:59], 0
	v_mov_b64_e32 v[60:61], 0
	v_mov_b64_e32 v[62:63], 0
	v_mov_b64_e32 v[64:65], 0
	v_mov_b64_e32 v[66:67], 0
	v_mov_b64_e32 v[68:69], 0
	v_mov_b64_e32 v[70:71], 0
	v_mov_b64_e32 v[72:73], 0
	v_mov_b64_e32 v[74:75], 0
	v_mov_b64_e32 v[76:77], 0
	v_mov_b64_e32 v[78:79], 0
	v_mov_b64_e32 v[80:81], 0
	v_mov_b64_e32 v[82:83], 0
	v_mov_b64_e32 v[84:85], 0
	v_mov_b64_e32 v[86:87], 0
	v_mov_b64_e32 v[88:89], 0
	v_mov_b64_e32 v[90:91], 0
	v_mov_b64_e32 v[92:93], 0
	v_mov_b64_e32 v[94:95], 0
	v_mov_b64_e32 v[96:97], 0
	v_mov_b64_e32 v[98:99], 0
	v_mov_b64_e32 v[100:101], 0
	v_mov_b64_e32 v[102:103], 0
	v_mov_b64_e32 v[104:105], 0
	v_mov_b64_e32 v[106:107], 0
	v_mov_b64_e32 v[108:109], 0
	v_mov_b64_e32 v[110:111], 0
	v_mov_b64_e32 v[112:113], 0
	v_mov_b64_e32 v[114:115], 0
	v_mov_b64_e32 v[116:117], 0
	v_mov_b64_e32 v[118:119], 0
	v_mov_b64_e32 v[120:121], 0
	v_mov_b64_e32 v[122:123], 0
	v_mov_b64_e32 v[124:125], 0
	v_mov_b64_e32 v[126:127], 0
	s_addc_u32 s75, s77, 0
	s_mov_b32 vcc_hi, -2
	s_barrier
	s_branch .LBB0_132

.LBB0_435:
	v_lshl_or_b32 v156, s91, 8, v160
	v_ashrrev_i32_e32 v157, 31, v156
	v_lshl_add_u64 v[128:129], v[156:157], 2, s[40:41]
	global_load_dwordx4 v[140:143], v[128:129], off
	global_load_dwordx4 v[136:139], v[128:129], off offset:16
	global_load_dwordx4 v[132:135], v[128:129], off offset:512
	s_nop 0
	global_load_dwordx4 v[128:131], v[128:129], off offset:528
	v_lshl_add_u32 v164, s90, 8, v158
	v_ashrrev_i32_e32 v165, 31, v164
	v_or_b32_e32 v166, 16, v164
	v_lshlrev_b64 v[170:171], 13, v[164:165]
	v_lshlrev_b64 v[172:173], 1, v[156:157]
	v_ashrrev_i32_e32 v167, 31, v166
	v_lshl_add_u64 v[156:157], s[8:9], 0, v[170:171]
	v_or_b32_e32 v168, 32, v164
	v_lshlrev_b64 v[166:167], 13, v[166:167]
	v_lshl_add_u64 v[156:157], v[156:157], 0, v[172:173]
	v_ashrrev_i32_e32 v169, 31, v168
	v_lshl_add_u64 v[166:167], s[8:9], 0, v[166:167]
	v_add_co_u32_e32 v174, vcc, s87, v156
	v_lshlrev_b64 v[168:169], 13, v[168:169]
	s_nop 0
	v_addc_co_u32_e32 v175, vcc, 0, v157, vcc
	v_lshl_add_u64 v[166:167], v[166:167], 0, v[172:173]
	v_lshl_add_u64 v[168:169], s[8:9], 0, v[168:169]
	v_lshl_add_u64 v[170:171], v[156:157], 0, s[54:55]
	v_lshl_add_u64 v[176:177], v[166:167], 0, s[54:55]
	v_add_co_u32_e32 v166, vcc, s87, v166
	v_lshl_add_u64 v[168:169], v[168:169], 0, v[172:173]
	s_nop 0
	v_addc_co_u32_e32 v167, vcc, 0, v167, vcc
	v_lshl_add_u64 v[178:179], v[168:169], 0, s[54:55]
	v_add_co_u32_e32 v168, vcc, s87, v168
	s_mov_b32 s3, 0x101000
	s_nop 0
	v_addc_co_u32_e32 v169, vcc, 0, v169, vcc
	s_mov_b64 s[16:17], 0x101000
	s_waitcnt vmcnt(0)
	v_pk_mul_f32 v[124:125], v[124:125], v[140:141]
	v_pk_mul_f32 v[126:127], v[126:127], v[142:143]
	v_pk_mul_f32 v[122:123], v[122:123], v[138:139]
	v_pk_mul_f32 v[182:183], v[80:81], v[128:129]
	v_cvt_pk_bf16_f32 v80, v124, v125
	v_pk_mul_f32 v[120:121], v[120:121], v[136:137]
	v_pk_mul_f32 v[104:105], v[104:105], v[132:133]
	v_pk_mul_f32 v[180:181], v[82:83], v[130:131]
	v_cvt_pk_bf16_f32 v81, v126, v127
	v_cvt_pk_bf16_f32 v82, v120, v121
	v_cvt_pk_bf16_f32 v83, v122, v123
	global_store_dwordx4 v[174:175], v[80:83], off
	v_pk_mul_f32 v[106:107], v[106:107], v[134:135]
	v_pk_mul_f32 v[98:99], v[98:99], v[130:131]
	v_cvt_pk_bf16_f32 v80, v104, v105
	v_pk_mul_f32 v[96:97], v[96:97], v[128:129]
	v_pk_mul_f32 v[116:117], v[116:117], v[140:141]
	v_cvt_pk_bf16_f32 v81, v106, v107
	v_cvt_pk_bf16_f32 v82, v96, v97
	v_cvt_pk_bf16_f32 v83, v98, v99
	global_store_dwordx4 v[170:171], v[80:83], off offset:256
	v_pk_mul_f32 v[118:119], v[118:119], v[142:143]
	v_pk_mul_f32 v[114:115], v[114:115], v[138:139]
	v_cvt_pk_bf16_f32 v80, v116, v117
	v_pk_mul_f32 v[112:113], v[112:113], v[136:137]
	v_pk_mul_f32 v[92:93], v[92:93], v[132:133]
	v_cvt_pk_bf16_f32 v81, v118, v119
	v_cvt_pk_bf16_f32 v82, v112, v113
	v_cvt_pk_bf16_f32 v83, v114, v115
	global_store_dwordx4 v[166:167], v[80:83], off
	v_pk_mul_f32 v[94:95], v[94:95], v[134:135]
	v_pk_mul_f32 v[90:91], v[90:91], v[130:131]
	v_cvt_pk_bf16_f32 v80, v92, v93
	v_pk_mul_f32 v[88:89], v[88:89], v[128:129]
	v_pk_mul_f32 v[108:109], v[108:109], v[140:141]
	v_cvt_pk_bf16_f32 v81, v94, v95
	v_cvt_pk_bf16_f32 v82, v88, v89
	v_cvt_pk_bf16_f32 v83, v90, v91
	global_store_dwordx4 v[176:177], v[80:83], off offset:256
	v_pk_mul_f32 v[110:111], v[110:111], v[142:143]
	v_pk_mul_f32 v[102:103], v[102:103], v[138:139]
	v_cvt_pk_bf16_f32 v80, v108, v109
	v_pk_mul_f32 v[100:101], v[100:101], v[136:137]
	v_pk_mul_f32 v[84:85], v[84:85], v[132:133]
	v_cvt_pk_bf16_f32 v81, v110, v111
	v_cvt_pk_bf16_f32 v82, v100, v101
	v_cvt_pk_bf16_f32 v83, v102, v103
	global_store_dwordx4 v[168:169], v[80:83], off
	v_pk_mul_f32 v[86:87], v[86:87], v[134:135]
	v_pk_mul_f32 v[76:77], v[76:77], v[140:141]
	v_cvt_pk_bf16_f32 v80, v84, v85
	v_cvt_pk_bf16_f32 v81, v86, v87
	v_cvt_pk_bf16_f32 v82, v182, v183
	v_cvt_pk_bf16_f32 v83, v180, v181
	global_store_dwordx4 v[178:179], v[80:83], off offset:256
	v_pk_mul_f32 v[78:79], v[78:79], v[142:143]
	v_pk_mul_f32 v[70:71], v[70:71], v[134:135]
	v_or_b32_e32 v80, 48, v164
	v_ashrrev_i32_e32 v81, 31, v80
	v_pk_mul_f32 v[82:83], v[74:75], v[138:139]
	v_pk_mul_f32 v[74:75], v[72:73], v[136:137]
	v_cvt_pk_bf16_f32 v72, v76, v77
	v_lshlrev_b64 v[76:77], 13, v[80:81]
	v_lshl_add_u64 v[76:77], s[8:9], 0, v[76:77]
	v_lshl_add_u64 v[76:77], v[76:77], 0, v[172:173]
	v_cvt_pk_bf16_f32 v73, v78, v79
	v_lshl_add_u64 v[78:79], v[76:77], 0, s[54:55]
	v_add_co_u32_e32 v76, vcc, s87, v76
	v_cvt_pk_bf16_f32 v74, v74, v75
	v_cvt_pk_bf16_f32 v75, v82, v83
	v_pk_mul_f32 v[68:69], v[68:69], v[132:133]
	s_nop 0
	v_addc_co_u32_e32 v77, vcc, 0, v77, vcc
	global_store_dwordx4 v[76:77], v[72:75], off
	v_pk_mul_f32 v[62:63], v[62:63], v[142:143]
	v_pk_mul_f32 v[60:61], v[60:61], v[140:141]
	v_pk_mul_f32 v[72:73], v[66:67], v[130:131]
	v_pk_mul_f32 v[66:67], v[64:65], v[128:129]
	v_cvt_pk_bf16_f32 v64, v68, v69
	v_cvt_pk_bf16_f32 v65, v70, v71
	v_pk_mul_f32 v[54:55], v[54:55], v[134:135]
	v_cvt_pk_bf16_f32 v66, v66, v67
	v_cvt_pk_bf16_f32 v67, v72, v73
	global_store_dwordx4 v[78:79], v[64:67], off offset:256
	v_pk_mul_f32 v[52:53], v[52:53], v[132:133]
	v_pk_mul_f32 v[38:39], v[38:39], v[134:135]
	v_pk_mul_f32 v[64:65], v[58:59], v[138:139]
	v_pk_mul_f32 v[58:59], v[56:57], v[136:137]
	v_cvt_pk_bf16_f32 v56, v60, v61
	v_cvt_pk_bf16_f32 v57, v62, v63
	v_add_co_u32_e32 v62, vcc, s3, v156
	v_cvt_pk_bf16_f32 v58, v58, v59
	v_cvt_pk_bf16_f32 v59, v64, v65
	v_lshl_add_u64 v[60:61], v[156:157], 0, s[16:17]
	s_nop 0
	v_addc_co_u32_e32 v63, vcc, 0, v157, vcc
	global_store_dwordx4 v[62:63], v[56:59], off
	s_mov_b32 s3, 0x121000
	s_mov_b64 s[16:17], 0x121000
	v_pk_mul_f32 v[56:57], v[46:47], v[130:131]
	v_pk_mul_f32 v[46:47], v[44:45], v[128:129]
	v_cvt_pk_bf16_f32 v44, v52, v53
	v_cvt_pk_bf16_f32 v45, v54, v55
	v_pk_mul_f32 v[36:37], v[36:37], v[132:133]
	v_cvt_pk_bf16_f32 v46, v46, v47
	v_cvt_pk_bf16_f32 v47, v56, v57
	global_store_dwordx4 v[60:61], v[44:47], off offset:256
	v_pk_mul_f32 v[22:23], v[22:23], v[134:135]
	v_pk_mul_f32 v[20:21], v[20:21], v[132:133]
	v_pk_mul_f32 v[46:47], v[48:49], v[140:141]
	v_pk_mul_f32 v[48:49], v[42:43], v[138:139]
	v_pk_mul_f32 v[42:43], v[40:41], v[136:137]
	v_cvt_pk_bf16_f32 v40, v46, v47
	v_add_co_u32_e32 v46, vcc, s3, v156
	v_pk_mul_f32 v[44:45], v[50:51], v[142:143]
	s_nop 0
	v_addc_co_u32_e32 v47, vcc, 0, v157, vcc
	v_cvt_pk_bf16_f32 v41, v44, v45
	v_cvt_pk_bf16_f32 v42, v42, v43
	v_cvt_pk_bf16_f32 v43, v48, v49
	global_store_dwordx4 v[46:47], v[40:43], off
	v_lshl_add_u64 v[44:45], v[156:157], 0, s[16:17]
	s_mov_b32 s3, 0x141000
	v_pk_mul_f32 v[40:41], v[30:31], v[130:131]
	v_pk_mul_f32 v[30:31], v[28:29], v[128:129]
	v_cvt_pk_bf16_f32 v28, v36, v37
	v_cvt_pk_bf16_f32 v29, v38, v39
	s_mov_b64 s[16:17], 0x141000
	v_cvt_pk_bf16_f32 v30, v30, v31
	v_cvt_pk_bf16_f32 v31, v40, v41
	global_store_dwordx4 v[44:45], v[28:31], off offset:256
	v_pk_mul_f32 v[6:7], v[6:7], v[134:135]
	v_pk_mul_f32 v[4:5], v[4:5], v[132:133]
	v_pk_mul_f32 v[30:31], v[32:33], v[140:141]
	v_pk_mul_f32 v[32:33], v[26:27], v[138:139]
	v_pk_mul_f32 v[26:27], v[24:25], v[136:137]
	v_cvt_pk_bf16_f32 v24, v30, v31
	v_add_co_u32_e32 v30, vcc, s3, v156
	v_pk_mul_f32 v[28:29], v[34:35], v[142:143]
	s_nop 0
	v_addc_co_u32_e32 v31, vcc, 0, v157, vcc
	v_cvt_pk_bf16_f32 v25, v28, v29
	v_cvt_pk_bf16_f32 v26, v26, v27
	v_cvt_pk_bf16_f32 v27, v32, v33
	global_store_dwordx4 v[30:31], v[24:27], off
	v_lshl_add_u64 v[28:29], v[156:157], 0, s[16:17]
	s_nop 0
	v_pk_mul_f32 v[24:25], v[14:15], v[130:131]
	v_pk_mul_f32 v[14:15], v[12:13], v[128:129]
	v_cvt_pk_bf16_f32 v12, v20, v21
	v_cvt_pk_bf16_f32 v13, v22, v23
	s_nop 0
	v_cvt_pk_bf16_f32 v14, v14, v15
	v_cvt_pk_bf16_f32 v15, v24, v25
	global_store_dwordx4 v[28:29], v[12:15], off offset:256
	s_nop 1
	v_pk_mul_f32 v[14:15], v[16:17], v[140:141]
	v_pk_mul_f32 v[16:17], v[10:11], v[138:139]
	v_pk_mul_f32 v[10:11], v[8:9], v[136:137]
	v_cvt_pk_bf16_f32 v8, v14, v15
	v_add_co_u32_e32 v14, vcc, s88, v156
	v_pk_mul_f32 v[12:13], v[18:19], v[142:143]
	s_nop 0
	v_addc_co_u32_e32 v15, vcc, 0, v157, vcc
	v_cvt_pk_bf16_f32 v9, v12, v13
	v_cvt_pk_bf16_f32 v10, v10, v11
	v_cvt_pk_bf16_f32 v11, v16, v17
	v_lshl_add_u64 v[12:13], v[156:157], 0, s[56:57]
	global_store_dwordx4 v[14:15], v[8:11], off
	s_andn2_b64 vcc, exec, s[58:59]
	s_mov_b64 s[58:59], -1
	v_pk_mul_f32 v[8:9], v[2:3], v[130:131]
	v_pk_mul_f32 v[2:3], v[0:1], v[128:129]
	v_cvt_pk_bf16_f32 v0, v4, v5
	v_cvt_pk_bf16_f32 v1, v6, v7
	s_nop 0
	v_cvt_pk_bf16_f32 v2, v2, v3
	v_cvt_pk_bf16_f32 v3, v8, v9
	global_store_dwordx4 v[12:13], v[0:3], off offset:256
	s_cbranch_vccnz .LBB0_430
	s_andn2_b64 vcc, exec, s[42:43]
	s_cbranch_vccnz .LBB0_429
	s_branch .Lthp4_429

.Lthp4_431:
	s_add_i32 s82, s82, 1
	s_mov_b32 s33, s0
	s_mov_b32 s91, s0
	s_mul_i32 s0, s82, s30
	s_mov_b64 s[70:71], s[4:5]
	s_add_i32 s4, s0, s2
	s_cmpk_lt_i32 s4, 0x200
	s_cselect_b64 s[58:59], -1, 0
	s_lshl_b32 s0, s4, 3
	s_mov_b64 s[16:17], s[38:39]
	s_mov_b32 s3, s78
	s_mov_b32 s38, s89
	s_mov_b32 s90, s78
	s_and_b32 s89, s0, 0xfffffc00
	s_ashr_i32 s0, s4, 6
	s_and_b32 s78, s4, 63
	s_and_b64 s[4:5], s[58:59], exec
	s_cselect_b32 s5, s89, s38
	s_cselect_b32 s38, s78, s3
	s_cselect_b32 s4, s0, s33
	s_ashr_i32 s39, s38, 31
	s_lshl_b64 s[38:39], s[38:39], 20
	s_add_u32 s3, s76, s38
	s_addc_u32 s33, s77, s39
	s_ashr_i32 s39, s5, 31
	s_add_u32 s38, s3, s5
	s_addc_u32 s39, s33, s39
	s_and_b64 s[72:73], s[58:59], exec
	s_cselect_b32 s93, s39, s17
	s_cselect_b32 s94, s38, s16
	s_ashr_i32 s5, s4, 31
	s_lshl_b64 s[4:5], s[4:5], 18
	s_add_u32 s4, s12, s4
	s_addc_u32 s5, s13, s5
	s_and_b64 s[72:73], s[58:59], exec
	s_cselect_b32 s95, s5, s71
	s_cselect_b32 s96, s4, s70
	s_add_u32 s97, s70, 0x1000
	s_addc_u32 vcc_lo, s71, 0
	s_add_u32 s70, s16, 0x80080
	v_mov_b64_e32 v[0:1], 0
	v_mov_b64_e32 v[2:3], 0
	v_mov_b64_e32 v[4:5], 0
	v_mov_b64_e32 v[6:7], 0
	v_mov_b64_e32 v[8:9], 0
	v_mov_b64_e32 v[10:11], 0
	v_mov_b64_e32 v[12:13], 0
	v_mov_b64_e32 v[14:15], 0
	v_mov_b64_e32 v[16:17], 0
	v_mov_b64_e32 v[18:19], 0
	v_mov_b64_e32 v[20:21], 0
	v_mov_b64_e32 v[22:23], 0
	v_mov_b64_e32 v[24:25], 0
	v_mov_b64_e32 v[26:27], 0
	v_mov_b64_e32 v[28:29], 0
	v_mov_b64_e32 v[30:31], 0
	v_mov_b64_e32 v[32:33], 0
	v_mov_b64_e32 v[34:35], 0
	v_mov_b64_e32 v[36:37], 0
	v_mov_b64_e32 v[38:39], 0
	v_mov_b64_e32 v[40:41], 0
	v_mov_b64_e32 v[42:43], 0
	v_mov_b64_e32 v[44:45], 0
	v_mov_b64_e32 v[46:47], 0
	v_mov_b64_e32 v[48:49], 0
	v_mov_b64_e32 v[50:51], 0
	v_mov_b64_e32 v[52:53], 0
	v_mov_b64_e32 v[54:55], 0
	v_mov_b64_e32 v[56:57], 0
	v_mov_b64_e32 v[58:59], 0
	v_mov_b64_e32 v[60:61], 0
	v_mov_b64_e32 v[62:63], 0
	v_mov_b64_e32 v[64:65], 0
	v_mov_b64_e32 v[66:67], 0
	v_mov_b64_e32 v[68:69], 0
	v_mov_b64_e32 v[70:71], 0
	v_mov_b64_e32 v[72:73], 0
	v_mov_b64_e32 v[74:75], 0
	v_mov_b64_e32 v[76:77], 0
	v_mov_b64_e32 v[78:79], 0
	v_mov_b64_e32 v[80:81], 0
	v_mov_b64_e32 v[82:83], 0
	v_mov_b64_e32 v[84:85], 0
	v_mov_b64_e32 v[86:87], 0
	v_mov_b64_e32 v[88:89], 0
	v_mov_b64_e32 v[90:91], 0
	v_mov_b64_e32 v[92:93], 0
	v_mov_b64_e32 v[94:95], 0
	v_mov_b64_e32 v[96:97], 0
	v_mov_b64_e32 v[98:99], 0
	v_mov_b64_e32 v[100:101], 0
	v_mov_b64_e32 v[102:103], 0
	v_mov_b64_e32 v[104:105], 0
	v_mov_b64_e32 v[106:107], 0
	v_mov_b64_e32 v[108:109], 0
	v_mov_b64_e32 v[110:111], 0
	v_mov_b64_e32 v[112:113], 0
	v_mov_b64_e32 v[114:115], 0
	v_mov_b64_e32 v[116:117], 0
	v_mov_b64_e32 v[118:119], 0
	v_mov_b64_e32 v[120:121], 0
	v_mov_b64_e32 v[122:123], 0
	v_mov_b64_e32 v[124:125], 0
	v_mov_b64_e32 v[126:127], 0
	s_addc_u32 s71, s17, 0
	s_mov_b32 vcc_hi, -2
	s_waitcnt vmcnt(0)
	s_barrier
	s_branch .LBB0_432

.LBB0_564:
	s_or_b64 exec, exec, s[48:49]
	s_andn2_b64 vcc, exec, s[6:7]
	s_mov_b64 s[6:7], -1
	s_cbranch_vccnz .LBB0_505
	s_andn2_b64 vcc, exec, s[12:13]
	s_cbranch_vccnz .LBB0_504
	s_branch .Lthp3_504

.Lthp3_512:
	s_ashr_i32 s43, s42, 31
	s_lshl_b64 s[16:17], s[42:43], 21
	s_add_u32 s44, s8, s16
	s_addc_u32 s45, s9, s17
	s_and_b64 s[16:17], s[6:7], exec
	s_cselect_b32 s43, s45, s59
	s_cselect_b32 s49, s44, s58
	s_ashr_i32 s41, s40, 31
	s_lshl_b64 s[16:17], s[40:41], 21
	s_add_u32 s46, s10, s16
	s_addc_u32 s47, s11, s17
	s_and_b64 s[16:17], s[6:7], exec
	s_cselect_b32 s41, s47, s57
	s_cselect_b32 s55, s46, s56
	s_add_u32 s80, s56, 0x1000
	s_addc_u32 s81, s57, 0
	s_add_u32 s56, s58, 0x100080
	v_mov_b64_e32 v[0:1], 0
	v_mov_b64_e32 v[2:3], 0
	v_mov_b64_e32 v[4:5], 0
	v_mov_b64_e32 v[6:7], 0
	v_mov_b64_e32 v[8:9], 0
	v_mov_b64_e32 v[10:11], 0
	v_mov_b64_e32 v[12:13], 0
	v_mov_b64_e32 v[14:15], 0
	v_mov_b64_e32 v[16:17], 0
	v_mov_b64_e32 v[18:19], 0
	v_mov_b64_e32 v[20:21], 0
	v_mov_b64_e32 v[22:23], 0
	v_mov_b64_e32 v[24:25], 0
	v_mov_b64_e32 v[26:27], 0
	v_mov_b64_e32 v[28:29], 0
	v_mov_b64_e32 v[30:31], 0
	v_mov_b64_e32 v[32:33], 0
	v_mov_b64_e32 v[34:35], 0
	v_mov_b64_e32 v[36:37], 0
	v_mov_b64_e32 v[38:39], 0
	v_mov_b64_e32 v[40:41], 0
	v_mov_b64_e32 v[42:43], 0
	v_mov_b64_e32 v[44:45], 0
	v_mov_b64_e32 v[46:47], 0
	v_mov_b64_e32 v[48:49], 0
	v_mov_b64_e32 v[50:51], 0
	v_mov_b64_e32 v[52:53], 0
	v_mov_b64_e32 v[54:55], 0
	v_mov_b64_e32 v[56:57], 0
	v_mov_b64_e32 v[58:59], 0
	v_mov_b64_e32 v[60:61], 0
	v_mov_b64_e32 v[62:63], 0
	v_mov_b64_e32 v[64:65], 0
	v_mov_b64_e32 v[66:67], 0
	v_mov_b64_e32 v[68:69], 0
	v_mov_b64_e32 v[70:71], 0
	v_mov_b64_e32 v[72:73], 0
	v_mov_b64_e32 v[74:75], 0
	v_mov_b64_e32 v[76:77], 0
	v_mov_b64_e32 v[78:79], 0
	v_mov_b64_e32 v[80:81], 0
	v_mov_b64_e32 v[82:83], 0
	v_mov_b64_e32 v[84:85], 0
	v_mov_b64_e32 v[86:87], 0
	v_mov_b64_e32 v[88:89], 0
	v_mov_b64_e32 v[90:91], 0
	v_mov_b64_e32 v[92:93], 0
	v_mov_b64_e32 v[94:95], 0
	v_mov_b64_e32 v[96:97], 0
	v_mov_b64_e32 v[98:99], 0
	v_mov_b64_e32 v[100:101], 0
	v_mov_b64_e32 v[102:103], 0
	v_mov_b64_e32 v[104:105], 0
	v_mov_b64_e32 v[106:107], 0
	v_mov_b64_e32 v[108:109], 0
	v_mov_b64_e32 v[110:111], 0
	v_mov_b64_e32 v[112:113], 0
	v_mov_b64_e32 v[114:115], 0
	v_mov_b64_e32 v[116:117], 0
	v_mov_b64_e32 v[118:119], 0
	v_mov_b64_e32 v[120:121], 0
	v_mov_b64_e32 v[122:123], 0
	v_mov_b64_e32 v[124:125], 0
	v_mov_b64_e32 v[126:127], 0
	s_addc_u32 s57, s59, 0
	s_mov_b32 s82, -2
	s_waitcnt lgkmcnt(0)
	s_barrier
	s_branch .LBB0_513

.LBB0_677:
	s_or_b64 exec, exec, s[62:63]
	s_andn2_b64 vcc, exec, s[8:9]
	s_mov_b64 s[8:9], -1
	s_cbranch_vccnz .LBB0_631
	s_and_b64 vcc, exec, s[10:11]
	s_cbranch_vccnz .LBB0_630
	s_branch .Lth_630

.Lth_638:
	s_ashr_i32 s55, s54, 31
	s_lshl_b64 s[16:17], s[54:55], 21
	s_add_u32 s56, s22, s16
	s_addc_u32 s57, s23, s17
	s_and_b64 s[16:17], s[8:9], exec
	s_cselect_b32 s11, s57, s15
	s_cselect_b32 s13, s56, s14
	s_ashr_i32 s53, s52, 31
	s_lshl_b64 s[16:17], s[52:53], 21
	s_add_u32 s58, s68, s16
	s_addc_u32 s59, s69, s17
	s_and_b64 s[16:17], s[8:9], exec
	s_cselect_b32 s53, s59, s61
	s_cselect_b32 s55, s58, s60
	s_add_u32 s90, s60, 0x1000
	v_mov_b64_e32 v[0:1], 0
	v_mov_b64_e32 v[2:3], 0
	v_mov_b64_e32 v[4:5], 0
	v_mov_b64_e32 v[6:7], 0
	v_mov_b64_e32 v[8:9], 0
	v_mov_b64_e32 v[10:11], 0
	v_mov_b64_e32 v[12:13], 0
	v_mov_b64_e32 v[14:15], 0
	v_mov_b64_e32 v[16:17], 0
	v_mov_b64_e32 v[18:19], 0
	v_mov_b64_e32 v[20:21], 0
	v_mov_b64_e32 v[22:23], 0
	v_mov_b64_e32 v[24:25], 0
	v_mov_b64_e32 v[26:27], 0
	v_mov_b64_e32 v[28:29], 0
	v_mov_b64_e32 v[30:31], 0
	v_mov_b64_e32 v[32:33], 0
	v_mov_b64_e32 v[34:35], 0
	v_mov_b64_e32 v[36:37], 0
	v_mov_b64_e32 v[38:39], 0
	v_mov_b64_e32 v[40:41], 0
	v_mov_b64_e32 v[42:43], 0
	v_mov_b64_e32 v[44:45], 0
	v_mov_b64_e32 v[46:47], 0
	v_mov_b64_e32 v[48:49], 0
	v_mov_b64_e32 v[50:51], 0
	v_mov_b64_e32 v[68:69], 0
	v_mov_b64_e32 v[70:71], 0
	v_mov_b64_e32 v[88:89], 0
	v_mov_b64_e32 v[90:91], 0
	v_mov_b64_e32 v[92:93], 0
	v_mov_b64_e32 v[94:95], 0
	v_mov_b64_e32 v[96:97], 0
	v_mov_b64_e32 v[98:99], 0
	v_mov_b64_e32 v[100:101], 0
	v_mov_b64_e32 v[102:103], 0
	v_mov_b64_e32 v[104:105], 0
	v_mov_b64_e32 v[106:107], 0
	v_mov_b64_e32 v[108:109], 0
	v_mov_b64_e32 v[110:111], 0
	v_mov_b64_e32 v[112:113], 0
	v_mov_b64_e32 v[114:115], 0
	v_mov_b64_e32 v[116:117], 0
	v_mov_b64_e32 v[118:119], 0
	v_mov_b64_e32 v[120:121], 0
	v_mov_b64_e32 v[122:123], 0
	v_mov_b64_e32 v[124:125], 0
	v_mov_b64_e32 v[126:127], 0
	v_mov_b64_e32 v[128:129], 0
	v_mov_b64_e32 v[130:131], 0
	v_mov_b64_e32 v[132:133], 0
	v_mov_b64_e32 v[134:135], 0
	v_mov_b64_e32 v[136:137], 0
	v_mov_b64_e32 v[138:139], 0
	v_mov_b64_e32 v[140:141], 0
	v_mov_b64_e32 v[142:143], 0
	v_mov_b64_e32 v[144:145], 0
	v_mov_b64_e32 v[146:147], 0
	v_mov_b64_e32 v[148:149], 0
	v_mov_b64_e32 v[150:151], 0
	v_mov_b64_e32 v[152:153], 0
	v_mov_b64_e32 v[154:155], 0
	v_mov_b64_e32 v[156:157], 0
	v_mov_b64_e32 v[158:159], 0
	s_addc_u32 s91, s61, 0
	s_mov_b32 s93, -2
	s_barrier
	s_branch .LBB0_639

.LBB0_790:
	s_or_b64 exec, exec, s[38:39]
	s_and_b64 vcc, exec, s[4:5]
	s_mov_b64 s[4:5], -1
	s_cbranch_vccnz .LBB0_759
	s_andn2_b64 vcc, exec, s[8:9]
	s_cbranch_vccnz .LBB0_758
	s_branch .Lthp7_758

.Lthp7_770:
	s_add_u32 s38, s38, 0x2b0800
	s_addc_u32 s39, s39, 0
	s_add_u32 s66, s40, 0x1000
	v_mov_b64_e32 v[0:1], 0
	v_mov_b64_e32 v[2:3], 0
	v_mov_b64_e32 v[4:5], 0
	v_mov_b64_e32 v[6:7], 0
	v_mov_b64_e32 v[8:9], 0
	v_mov_b64_e32 v[10:11], 0
	v_mov_b64_e32 v[12:13], 0
	v_mov_b64_e32 v[14:15], 0
	v_mov_b64_e32 v[16:17], 0
	v_mov_b64_e32 v[18:19], 0
	v_mov_b64_e32 v[20:21], 0
	v_mov_b64_e32 v[22:23], 0
	v_mov_b64_e32 v[24:25], 0
	v_mov_b64_e32 v[26:27], 0
	v_mov_b64_e32 v[28:29], 0
	v_mov_b64_e32 v[30:31], 0
	v_mov_b64_e32 v[32:33], 0
	v_mov_b64_e32 v[34:35], 0
	v_mov_b64_e32 v[36:37], 0
	v_mov_b64_e32 v[38:39], 0
	v_mov_b64_e32 v[40:41], 0
	v_mov_b64_e32 v[42:43], 0
	v_mov_b64_e32 v[44:45], 0
	v_mov_b64_e32 v[46:47], 0
	v_mov_b64_e32 v[48:49], 0
	v_mov_b64_e32 v[50:51], 0
	v_mov_b64_e32 v[52:53], 0
	v_mov_b64_e32 v[54:55], 0
	v_mov_b64_e32 v[56:57], 0
	v_mov_b64_e32 v[58:59], 0
	v_mov_b64_e32 v[60:61], 0
	v_mov_b64_e32 v[62:63], 0
	v_mov_b64_e32 v[64:65], 0
	v_mov_b64_e32 v[66:67], 0
	v_mov_b64_e32 v[68:69], 0
	v_mov_b64_e32 v[70:71], 0
	v_mov_b64_e32 v[72:73], 0
	v_mov_b64_e32 v[74:75], 0
	v_mov_b64_e32 v[76:77], 0
	v_mov_b64_e32 v[78:79], 0
	v_mov_b64_e32 v[80:81], 0
	v_mov_b64_e32 v[82:83], 0
	v_mov_b64_e32 v[84:85], 0
	v_mov_b64_e32 v[86:87], 0
	v_mov_b64_e32 v[88:89], 0
	v_mov_b64_e32 v[90:91], 0
	v_mov_b64_e32 v[92:93], 0
	v_mov_b64_e32 v[94:95], 0
	v_mov_b64_e32 v[96:97], 0
	v_mov_b64_e32 v[98:99], 0
	v_mov_b64_e32 v[100:101], 0
	v_mov_b64_e32 v[102:103], 0
	v_mov_b64_e32 v[104:105], 0
	v_mov_b64_e32 v[106:107], 0
	v_mov_b64_e32 v[108:109], 0
	v_mov_b64_e32 v[110:111], 0
	v_mov_b64_e32 v[112:113], 0
	v_mov_b64_e32 v[114:115], 0
	v_mov_b64_e32 v[116:117], 0
	v_mov_b64_e32 v[118:119], 0
	v_mov_b64_e32 v[120:121], 0
	v_mov_b64_e32 v[122:123], 0
	v_mov_b64_e32 v[124:125], 0
	v_mov_b64_e32 v[126:127], 0
	s_addc_u32 s67, s41, 0
	s_mov_b32 s68, -2
	s_waitcnt lgkmcnt(0)
	s_barrier
	s_branch .LBB0_771
